# batched silu(c) staging loads in the prologue, on top of previous
# baseline (speedup 1.0000x reference)
; #define LAS __attribute__((address_space(3)))
; __device__ __forceinline__ float sigmoidf_(float x) { return rcp(1.0f + ex2(-LOG2E * x)); }
; __device__ __forceinline__ void p0_mods(const Args& a, LAS unsigned char* lds, int wg, int G, int wave, int lane, int tid) {
;     LAS float* sc = (LAS float*)lds;
;     for (int i = tid; i < BATCH * D; i += 512) { const float x = a.in[I_C][i]; sc[i] = x * sigmoidf_(x); }
;     __syncthreads();
.LBB0_5:
	s_or_b64 exec, exec, s[2:3]
	s_lshr_b32 s69, s27, 6
	s_lshl_b32 s2, s96, 3
	s_add_i32 s33, s69, s2
	s_cmp_lt_i32 s18, 1
	v_writelane_b32 v250, s2, 36
	s_cselect_b64 s[2:3], -1, 0
	s_cmp_gt_i32 s19, 0
	s_cselect_b64 s[4:5], -1, 0
	s_and_b64 s[2:3], s[2:3], s[4:5]
	s_andn2_b64 vcc, exec, s[2:3]
	v_and_b32_e32 v1, 63, v0
	s_cbranch_vccnz .LBB0_82
	s_mov_b64 s[2:3], s[82:83]
	global_load_dword v10, v2, s[2:3]
	global_load_dword v11, v2, s[2:3] offset:2048
	s_add_u32 s2, s2, 0x1000
	s_addc_u32 s3, s3, 0
	global_load_dword v12, v2, s[2:3]
	global_load_dword v13, v2, s[2:3] offset:2048
	s_add_u32 s2, s2, 0x1000
	s_addc_u32 s3, s3, 0
	global_load_dword v14, v2, s[2:3]
	global_load_dword v15, v2, s[2:3] offset:2048
	s_add_u32 s2, s2, 0x1000
	s_addc_u32 s3, s3, 0
	global_load_dword v16, v2, s[2:3]
	global_load_dword v17, v2, s[2:3] offset:2048
	s_add_u32 s2, s2, 0x1000
	s_addc_u32 s3, s3, 0
	global_load_dword v18, v2, s[2:3]
	global_load_dword v19, v2, s[2:3] offset:2048
	s_add_u32 s2, s2, 0x1000
	s_addc_u32 s3, s3, 0
	global_load_dword v20, v2, s[2:3]
	global_load_dword v21, v2, s[2:3] offset:2048
	s_add_u32 s2, s2, 0x1000
	s_addc_u32 s3, s3, 0
	global_load_dword v22, v2, s[2:3]
	global_load_dword v23, v2, s[2:3] offset:2048
	s_add_u32 s2, s2, 0x1000
	s_addc_u32 s3, s3, 0
	global_load_dword v24, v2, s[2:3]
	global_load_dword v25, v2, s[2:3] offset:2048
	s_add_u32 s2, s2, 0x1000
	s_addc_u32 s3, s3, 0
	global_load_dword v26, v2, s[2:3]
	global_load_dword v27, v2, s[2:3] offset:2048
	s_add_u32 s2, s2, 0x1000
	s_addc_u32 s3, s3, 0
	global_load_dword v28, v2, s[2:3]
	global_load_dword v29, v2, s[2:3] offset:2048
	s_add_u32 s2, s2, 0x1000
	s_addc_u32 s3, s3, 0
	global_load_dword v30, v2, s[2:3]
	global_load_dword v31, v2, s[2:3] offset:2048
	s_add_u32 s2, s2, 0x1000
	s_addc_u32 s3, s3, 0
	global_load_dword v32, v2, s[2:3]
	global_load_dword v33, v2, s[2:3] offset:2048
	s_add_u32 s2, s2, 0x1000
	s_addc_u32 s3, s3, 0
	global_load_dword v34, v2, s[2:3]
	global_load_dword v35, v2, s[2:3] offset:2048
	s_add_u32 s2, s2, 0x1000
	s_addc_u32 s3, s3, 0
	global_load_dword v36, v2, s[2:3]
	global_load_dword v37, v2, s[2:3] offset:2048
	s_add_u32 s2, s2, 0x1000
	s_addc_u32 s3, s3, 0
	global_load_dword v38, v2, s[2:3]
	global_load_dword v39, v2, s[2:3] offset:2048
	s_add_u32 s2, s2, 0x1000
	s_addc_u32 s3, s3, 0
	global_load_dword v40, v2, s[2:3]
	global_load_dword v41, v2, s[2:3] offset:2048
	s_add_u32 s2, s2, 0x1000
	s_addc_u32 s3, s3, 0
	global_load_dword v42, v2, s[2:3]
	global_load_dword v43, v2, s[2:3] offset:2048
	s_add_u32 s2, s2, 0x1000
	s_addc_u32 s3, s3, 0
	global_load_dword v44, v2, s[2:3]
	global_load_dword v45, v2, s[2:3] offset:2048
	s_add_u32 s2, s2, 0x1000
	s_addc_u32 s3, s3, 0
	global_load_dword v46, v2, s[2:3]
	global_load_dword v47, v2, s[2:3] offset:2048
	s_add_u32 s2, s2, 0x1000
	s_addc_u32 s3, s3, 0
	global_load_dword v48, v2, s[2:3]
	global_load_dword v49, v2, s[2:3] offset:2048
	s_add_u32 s2, s2, 0x1000
	s_addc_u32 s3, s3, 0
	global_load_dword v50, v2, s[2:3]
	global_load_dword v51, v2, s[2:3] offset:2048
	s_add_u32 s2, s2, 0x1000
	s_addc_u32 s3, s3, 0
	global_load_dword v52, v2, s[2:3]
	global_load_dword v53, v2, s[2:3] offset:2048
	s_add_u32 s2, s2, 0x1000
	s_addc_u32 s3, s3, 0
	global_load_dword v54, v2, s[2:3]
	global_load_dword v55, v2, s[2:3] offset:2048
	s_add_u32 s2, s2, 0x1000
	s_addc_u32 s3, s3, 0
	global_load_dword v56, v2, s[2:3]
	global_load_dword v57, v2, s[2:3] offset:2048
	s_add_u32 s2, s2, 0x1000
	s_addc_u32 s3, s3, 0
	global_load_dword v58, v2, s[2:3]
	global_load_dword v59, v2, s[2:3] offset:2048
	s_add_u32 s2, s2, 0x1000
	s_addc_u32 s3, s3, 0
	global_load_dword v60, v2, s[2:3]
	global_load_dword v61, v2, s[2:3] offset:2048
	s_add_u32 s2, s2, 0x1000
	s_addc_u32 s3, s3, 0
	global_load_dword v62, v2, s[2:3]
	global_load_dword v63, v2, s[2:3] offset:2048
	s_add_u32 s2, s2, 0x1000
	s_addc_u32 s3, s3, 0
	global_load_dword v64, v2, s[2:3]
	global_load_dword v65, v2, s[2:3] offset:2048
	s_add_u32 s2, s2, 0x1000
	s_addc_u32 s3, s3, 0
	global_load_dword v66, v2, s[2:3]
	global_load_dword v67, v2, s[2:3] offset:2048
	s_add_u32 s2, s2, 0x1000
	s_addc_u32 s3, s3, 0
	global_load_dword v68, v2, s[2:3]
	global_load_dword v69, v2, s[2:3] offset:2048
	s_add_u32 s2, s2, 0x1000
	s_addc_u32 s3, s3, 0
	global_load_dword v70, v2, s[2:3]
	global_load_dword v71, v2, s[2:3] offset:2048
	s_add_u32 s2, s2, 0x1000
	s_addc_u32 s3, s3, 0
	global_load_dword v72, v2, s[2:3]
	global_load_dword v73, v2, s[2:3] offset:2048
	s_waitcnt vmcnt(63)
	v_mul_f32_e32 v8, 0xbfb8aa3b, v10
	v_exp_f32_e32 v8, v8
	s_nop 0
	v_add_f32_e32 v8, 1.0, v8
	v_rcp_f32_e32 v8, v8
	s_nop 0
	v_mul_f32_e32 v10, v10, v8
	ds_write_b32 v7, v10
	s_waitcnt vmcnt(62)
	v_mul_f32_e32 v8, 0xbfb8aa3b, v11
	v_exp_f32_e32 v8, v8
	s_nop 0
	v_add_f32_e32 v8, 1.0, v8
	v_rcp_f32_e32 v8, v8
	s_nop 0
	v_mul_f32_e32 v11, v11, v8
	ds_write_b32 v7, v11 offset:2048
	s_waitcnt vmcnt(61)
	v_mul_f32_e32 v8, 0xbfb8aa3b, v12
	v_exp_f32_e32 v8, v8
	s_nop 0
	v_add_f32_e32 v8, 1.0, v8
	v_rcp_f32_e32 v8, v8
	s_nop 0
	v_mul_f32_e32 v12, v12, v8
	ds_write_b32 v7, v12 offset:4096
	s_waitcnt vmcnt(60)
	v_mul_f32_e32 v8, 0xbfb8aa3b, v13
	v_exp_f32_e32 v8, v8
	s_nop 0
	v_add_f32_e32 v8, 1.0, v8
	v_rcp_f32_e32 v8, v8
	s_nop 0
	v_mul_f32_e32 v13, v13, v8
	ds_write_b32 v7, v13 offset:6144
	s_waitcnt vmcnt(59)
	v_mul_f32_e32 v8, 0xbfb8aa3b, v14
	v_exp_f32_e32 v8, v8
	s_nop 0
	v_add_f32_e32 v8, 1.0, v8
	v_rcp_f32_e32 v8, v8
	s_nop 0
	v_mul_f32_e32 v14, v14, v8
	ds_write_b32 v7, v14 offset:8192
	s_waitcnt vmcnt(58)
; #define LAS __attribute__((address_space(3)))
; __device__ __forceinline__ float sigmoidf_(float x) { return rcp(1.0f + ex2(-LOG2E * x)); }
; __device__ __forceinline__ void p0_mods(const Args& a, LAS unsigned char* lds, int wg, int G, int wave, int lane, int tid) {
;     LAS float* sc = (LAS float*)lds;
;     for (int i = tid; i < BATCH * D; i += 512) { const float x = a.in[I_C][i]; sc[i] = x * sigmoidf_(x); }
;     __syncthreads();
	v_mul_f32_e32 v8, 0xbfb8aa3b, v15
	v_exp_f32_e32 v8, v8
	s_nop 0
	v_add_f32_e32 v8, 1.0, v8
	v_rcp_f32_e32 v8, v8
	s_nop 0
	v_mul_f32_e32 v15, v15, v8
	ds_write_b32 v7, v15 offset:10240
	s_waitcnt vmcnt(57)
	v_mul_f32_e32 v8, 0xbfb8aa3b, v16
	v_exp_f32_e32 v8, v8
	s_nop 0
	v_add_f32_e32 v8, 1.0, v8
	v_rcp_f32_e32 v8, v8
	s_nop 0
	v_mul_f32_e32 v16, v16, v8
	ds_write_b32 v7, v16 offset:12288
	s_waitcnt vmcnt(56)
	v_mul_f32_e32 v8, 0xbfb8aa3b, v17
	v_exp_f32_e32 v8, v8
	s_nop 0
	v_add_f32_e32 v8, 1.0, v8
	v_rcp_f32_e32 v8, v8
	s_nop 0
	v_mul_f32_e32 v17, v17, v8
	ds_write_b32 v7, v17 offset:14336
	s_waitcnt vmcnt(55)
	v_mul_f32_e32 v8, 0xbfb8aa3b, v18
	v_exp_f32_e32 v8, v8
	s_nop 0
	v_add_f32_e32 v8, 1.0, v8
	v_rcp_f32_e32 v8, v8
	s_nop 0
	v_mul_f32_e32 v18, v18, v8
	ds_write_b32 v7, v18 offset:16384
	s_waitcnt vmcnt(54)
	v_mul_f32_e32 v8, 0xbfb8aa3b, v19
	v_exp_f32_e32 v8, v8
	s_nop 0
	v_add_f32_e32 v8, 1.0, v8
	v_rcp_f32_e32 v8, v8
	s_nop 0
	v_mul_f32_e32 v19, v19, v8
	ds_write_b32 v7, v19 offset:18432
	s_waitcnt vmcnt(53)
	v_mul_f32_e32 v8, 0xbfb8aa3b, v20
	v_exp_f32_e32 v8, v8
	s_nop 0
	v_add_f32_e32 v8, 1.0, v8
	v_rcp_f32_e32 v8, v8
	s_nop 0
	v_mul_f32_e32 v20, v20, v8
	ds_write_b32 v7, v20 offset:20480
	s_waitcnt vmcnt(52)
	v_mul_f32_e32 v8, 0xbfb8aa3b, v21
	v_exp_f32_e32 v8, v8
	s_nop 0
	v_add_f32_e32 v8, 1.0, v8
	v_rcp_f32_e32 v8, v8
	s_nop 0
	v_mul_f32_e32 v21, v21, v8
	ds_write_b32 v7, v21 offset:22528
	s_waitcnt vmcnt(51)
	v_mul_f32_e32 v8, 0xbfb8aa3b, v22
	v_exp_f32_e32 v8, v8
	s_nop 0
	v_add_f32_e32 v8, 1.0, v8
	v_rcp_f32_e32 v8, v8
	s_nop 0
	v_mul_f32_e32 v22, v22, v8
	ds_write_b32 v7, v22 offset:24576
	s_waitcnt vmcnt(50)
	v_mul_f32_e32 v8, 0xbfb8aa3b, v23
	v_exp_f32_e32 v8, v8
	s_nop 0
	v_add_f32_e32 v8, 1.0, v8
	v_rcp_f32_e32 v8, v8
	s_nop 0
	v_mul_f32_e32 v23, v23, v8
	ds_write_b32 v7, v23 offset:26624
	s_waitcnt vmcnt(49)
	v_mul_f32_e32 v8, 0xbfb8aa3b, v24
	v_exp_f32_e32 v8, v8
	s_nop 0
	v_add_f32_e32 v8, 1.0, v8
	v_rcp_f32_e32 v8, v8
	s_nop 0
	v_mul_f32_e32 v24, v24, v8
	ds_write_b32 v7, v24 offset:28672
	s_waitcnt vmcnt(48)
	v_mul_f32_e32 v8, 0xbfb8aa3b, v25
	v_exp_f32_e32 v8, v8
	s_nop 0
	v_add_f32_e32 v8, 1.0, v8
	v_rcp_f32_e32 v8, v8
	s_nop 0
	v_mul_f32_e32 v25, v25, v8
	ds_write_b32 v7, v25 offset:30720
	s_waitcnt vmcnt(47)
	v_mul_f32_e32 v8, 0xbfb8aa3b, v26
	v_exp_f32_e32 v8, v8
	s_nop 0
	v_add_f32_e32 v8, 1.0, v8
	v_rcp_f32_e32 v8, v8
	s_nop 0
	v_mul_f32_e32 v26, v26, v8
	ds_write_b32 v7, v26 offset:32768
	s_waitcnt vmcnt(46)
	v_mul_f32_e32 v8, 0xbfb8aa3b, v27
	v_exp_f32_e32 v8, v8
	s_nop 0
	v_add_f32_e32 v8, 1.0, v8
	v_rcp_f32_e32 v8, v8
	s_nop 0
	v_mul_f32_e32 v27, v27, v8
	ds_write_b32 v7, v27 offset:34816
	s_waitcnt vmcnt(45)
	v_mul_f32_e32 v8, 0xbfb8aa3b, v28
	v_exp_f32_e32 v8, v8
	s_nop 0
	v_add_f32_e32 v8, 1.0, v8
	v_rcp_f32_e32 v8, v8
	s_nop 0
	v_mul_f32_e32 v28, v28, v8
	ds_write_b32 v7, v28 offset:36864
	s_waitcnt vmcnt(44)
	v_mul_f32_e32 v8, 0xbfb8aa3b, v29
	v_exp_f32_e32 v8, v8
	s_nop 0
	v_add_f32_e32 v8, 1.0, v8
	v_rcp_f32_e32 v8, v8
	s_nop 0
	v_mul_f32_e32 v29, v29, v8
	ds_write_b32 v7, v29 offset:38912
	s_waitcnt vmcnt(43)
	v_mul_f32_e32 v8, 0xbfb8aa3b, v30
	v_exp_f32_e32 v8, v8
	s_nop 0
	v_add_f32_e32 v8, 1.0, v8
	v_rcp_f32_e32 v8, v8
	s_nop 0
	v_mul_f32_e32 v30, v30, v8
	ds_write_b32 v7, v30 offset:40960
	s_waitcnt vmcnt(42)
	v_mul_f32_e32 v8, 0xbfb8aa3b, v31
	v_exp_f32_e32 v8, v8
	s_nop 0
	v_add_f32_e32 v8, 1.0, v8
	v_rcp_f32_e32 v8, v8
	s_nop 0
	v_mul_f32_e32 v31, v31, v8
	ds_write_b32 v7, v31 offset:43008
	s_waitcnt vmcnt(41)
	v_mul_f32_e32 v8, 0xbfb8aa3b, v32
	v_exp_f32_e32 v8, v8
	s_nop 0
	v_add_f32_e32 v8, 1.0, v8
	v_rcp_f32_e32 v8, v8
	s_nop 0
	v_mul_f32_e32 v32, v32, v8
	ds_write_b32 v7, v32 offset:45056
	s_waitcnt vmcnt(40)
	v_mul_f32_e32 v8, 0xbfb8aa3b, v33
	v_exp_f32_e32 v8, v8
	s_nop 0
	v_add_f32_e32 v8, 1.0, v8
	v_rcp_f32_e32 v8, v8
	s_nop 0
	v_mul_f32_e32 v33, v33, v8
	ds_write_b32 v7, v33 offset:47104
	s_waitcnt vmcnt(39)
	v_mul_f32_e32 v8, 0xbfb8aa3b, v34
	v_exp_f32_e32 v8, v8
	s_nop 0
	v_add_f32_e32 v8, 1.0, v8
	v_rcp_f32_e32 v8, v8
	s_nop 0
	v_mul_f32_e32 v34, v34, v8
	ds_write_b32 v7, v34 offset:49152
	s_waitcnt vmcnt(38)
	v_mul_f32_e32 v8, 0xbfb8aa3b, v35
	v_exp_f32_e32 v8, v8
	s_nop 0
	v_add_f32_e32 v8, 1.0, v8
	v_rcp_f32_e32 v8, v8
	s_nop 0
	v_mul_f32_e32 v35, v35, v8
	ds_write_b32 v7, v35 offset:51200
	s_waitcnt vmcnt(37)
	v_mul_f32_e32 v8, 0xbfb8aa3b, v36
	v_exp_f32_e32 v8, v8
	s_nop 0
	v_add_f32_e32 v8, 1.0, v8
	v_rcp_f32_e32 v8, v8
	s_nop 0
	v_mul_f32_e32 v36, v36, v8
	ds_write_b32 v7, v36 offset:53248
	s_waitcnt vmcnt(36)
	v_mul_f32_e32 v8, 0xbfb8aa3b, v37
	v_exp_f32_e32 v8, v8
	s_nop 0
	v_add_f32_e32 v8, 1.0, v8
	v_rcp_f32_e32 v8, v8
	s_nop 0
	v_mul_f32_e32 v37, v37, v8
	ds_write_b32 v7, v37 offset:55296
	s_waitcnt vmcnt(35)
	v_mul_f32_e32 v8, 0xbfb8aa3b, v38
	v_exp_f32_e32 v8, v8
	s_nop 0
	v_add_f32_e32 v8, 1.0, v8
	v_rcp_f32_e32 v8, v8
	s_nop 0
	v_mul_f32_e32 v38, v38, v8
	ds_write_b32 v7, v38 offset:57344
	s_waitcnt vmcnt(34)
	v_mul_f32_e32 v8, 0xbfb8aa3b, v39
	v_exp_f32_e32 v8, v8
	s_nop 0
	v_add_f32_e32 v8, 1.0, v8
	v_rcp_f32_e32 v8, v8
	s_nop 0
	v_mul_f32_e32 v39, v39, v8
	ds_write_b32 v7, v39 offset:59392
	s_waitcnt vmcnt(33)
	v_mul_f32_e32 v8, 0xbfb8aa3b, v40
	v_exp_f32_e32 v8, v8
	s_nop 0
	v_add_f32_e32 v8, 1.0, v8
	v_rcp_f32_e32 v8, v8
	s_nop 0
	v_mul_f32_e32 v40, v40, v8
	ds_write_b32 v7, v40 offset:61440
	s_waitcnt vmcnt(32)
	v_mul_f32_e32 v8, 0xbfb8aa3b, v41
	v_exp_f32_e32 v8, v8
	s_nop 0
	v_add_f32_e32 v8, 1.0, v8
	v_rcp_f32_e32 v8, v8
	s_nop 0
	v_mul_f32_e32 v41, v41, v8
	ds_write_b32 v7, v41 offset:63488
	s_waitcnt vmcnt(31)
; #define LAS __attribute__((address_space(3)))
; __device__ __forceinline__ float sigmoidf_(float x) { return rcp(1.0f + ex2(-LOG2E * x)); }
; __device__ __forceinline__ void p0_mods(const Args& a, LAS unsigned char* lds, int wg, int G, int wave, int lane, int tid) {
;     LAS float* sc = (LAS float*)lds;
;     for (int i = tid; i < BATCH * D; i += 512) { const float x = a.in[I_C][i]; sc[i] = x * sigmoidf_(x); }
;     __syncthreads();
	v_mul_f32_e32 v8, 0xbfb8aa3b, v42
	v_exp_f32_e32 v8, v8
	s_nop 0
	v_add_f32_e32 v8, 1.0, v8
	v_rcp_f32_e32 v8, v8
	s_nop 0
	v_mul_f32_e32 v42, v42, v8
	v_add_u32_e32 v7, 0x10000, v7
	ds_write_b32 v7, v42
	s_waitcnt vmcnt(30)
	v_mul_f32_e32 v8, 0xbfb8aa3b, v43
	v_exp_f32_e32 v8, v8
	s_nop 0
	v_add_f32_e32 v8, 1.0, v8
	v_rcp_f32_e32 v8, v8
	s_nop 0
	v_mul_f32_e32 v43, v43, v8
	ds_write_b32 v7, v43 offset:2048
	s_waitcnt vmcnt(29)
	v_mul_f32_e32 v8, 0xbfb8aa3b, v44
	v_exp_f32_e32 v8, v8
	s_nop 0
	v_add_f32_e32 v8, 1.0, v8
	v_rcp_f32_e32 v8, v8
	s_nop 0
	v_mul_f32_e32 v44, v44, v8
	ds_write_b32 v7, v44 offset:4096
	s_waitcnt vmcnt(28)
	v_mul_f32_e32 v8, 0xbfb8aa3b, v45
	v_exp_f32_e32 v8, v8
	s_nop 0
	v_add_f32_e32 v8, 1.0, v8
	v_rcp_f32_e32 v8, v8
	s_nop 0
	v_mul_f32_e32 v45, v45, v8
	ds_write_b32 v7, v45 offset:6144
	s_waitcnt vmcnt(27)
	v_mul_f32_e32 v8, 0xbfb8aa3b, v46
	v_exp_f32_e32 v8, v8
	s_nop 0
	v_add_f32_e32 v8, 1.0, v8
	v_rcp_f32_e32 v8, v8
	s_nop 0
	v_mul_f32_e32 v46, v46, v8
	ds_write_b32 v7, v46 offset:8192
	s_waitcnt vmcnt(26)
	v_mul_f32_e32 v8, 0xbfb8aa3b, v47
	v_exp_f32_e32 v8, v8
	s_nop 0
	v_add_f32_e32 v8, 1.0, v8
	v_rcp_f32_e32 v8, v8
	s_nop 0
	v_mul_f32_e32 v47, v47, v8
	ds_write_b32 v7, v47 offset:10240
	s_waitcnt vmcnt(25)
	v_mul_f32_e32 v8, 0xbfb8aa3b, v48
	v_exp_f32_e32 v8, v8
	s_nop 0
	v_add_f32_e32 v8, 1.0, v8
	v_rcp_f32_e32 v8, v8
	s_nop 0
	v_mul_f32_e32 v48, v48, v8
	ds_write_b32 v7, v48 offset:12288
	s_waitcnt vmcnt(24)
	v_mul_f32_e32 v8, 0xbfb8aa3b, v49
	v_exp_f32_e32 v8, v8
	s_nop 0
	v_add_f32_e32 v8, 1.0, v8
	v_rcp_f32_e32 v8, v8
	s_nop 0
	v_mul_f32_e32 v49, v49, v8
	ds_write_b32 v7, v49 offset:14336
	s_waitcnt vmcnt(23)
	v_mul_f32_e32 v8, 0xbfb8aa3b, v50
	v_exp_f32_e32 v8, v8
	s_nop 0
	v_add_f32_e32 v8, 1.0, v8
	v_rcp_f32_e32 v8, v8
	s_nop 0
	v_mul_f32_e32 v50, v50, v8
	ds_write_b32 v7, v50 offset:16384
	s_waitcnt vmcnt(22)
	v_mul_f32_e32 v8, 0xbfb8aa3b, v51
	v_exp_f32_e32 v8, v8
	s_nop 0
	v_add_f32_e32 v8, 1.0, v8
	v_rcp_f32_e32 v8, v8
	s_nop 0
	v_mul_f32_e32 v51, v51, v8
	ds_write_b32 v7, v51 offset:18432
	s_waitcnt vmcnt(21)
	v_mul_f32_e32 v8, 0xbfb8aa3b, v52
	v_exp_f32_e32 v8, v8
	s_nop 0
	v_add_f32_e32 v8, 1.0, v8
	v_rcp_f32_e32 v8, v8
	s_nop 0
	v_mul_f32_e32 v52, v52, v8
	ds_write_b32 v7, v52 offset:20480
	s_waitcnt vmcnt(20)
	v_mul_f32_e32 v8, 0xbfb8aa3b, v53
	v_exp_f32_e32 v8, v8
	s_nop 0
	v_add_f32_e32 v8, 1.0, v8
	v_rcp_f32_e32 v8, v8
	s_nop 0
	v_mul_f32_e32 v53, v53, v8
	ds_write_b32 v7, v53 offset:22528
	s_waitcnt vmcnt(19)
	v_mul_f32_e32 v8, 0xbfb8aa3b, v54
	v_exp_f32_e32 v8, v8
	s_nop 0
	v_add_f32_e32 v8, 1.0, v8
	v_rcp_f32_e32 v8, v8
	s_nop 0
	v_mul_f32_e32 v54, v54, v8
	ds_write_b32 v7, v54 offset:24576
	s_waitcnt vmcnt(18)
	v_mul_f32_e32 v8, 0xbfb8aa3b, v55
	v_exp_f32_e32 v8, v8
	s_nop 0
	v_add_f32_e32 v8, 1.0, v8
	v_rcp_f32_e32 v8, v8
	s_nop 0
	v_mul_f32_e32 v55, v55, v8
	ds_write_b32 v7, v55 offset:26624
	s_waitcnt vmcnt(17)
	v_mul_f32_e32 v8, 0xbfb8aa3b, v56
	v_exp_f32_e32 v8, v8
	s_nop 0
	v_add_f32_e32 v8, 1.0, v8
	v_rcp_f32_e32 v8, v8
	s_nop 0
	v_mul_f32_e32 v56, v56, v8
	ds_write_b32 v7, v56 offset:28672
	s_waitcnt vmcnt(16)
	v_mul_f32_e32 v8, 0xbfb8aa3b, v57
	v_exp_f32_e32 v8, v8
	s_nop 0
	v_add_f32_e32 v8, 1.0, v8
	v_rcp_f32_e32 v8, v8
	s_nop 0
	v_mul_f32_e32 v57, v57, v8
	ds_write_b32 v7, v57 offset:30720
	s_waitcnt vmcnt(15)
	v_mul_f32_e32 v8, 0xbfb8aa3b, v58
	v_exp_f32_e32 v8, v8
	s_nop 0
	v_add_f32_e32 v8, 1.0, v8
	v_rcp_f32_e32 v8, v8
	s_nop 0
	v_mul_f32_e32 v58, v58, v8
	ds_write_b32 v7, v58 offset:32768
	s_waitcnt vmcnt(14)
	v_mul_f32_e32 v8, 0xbfb8aa3b, v59
	v_exp_f32_e32 v8, v8
	s_nop 0
	v_add_f32_e32 v8, 1.0, v8
	v_rcp_f32_e32 v8, v8
	s_nop 0
	v_mul_f32_e32 v59, v59, v8
	ds_write_b32 v7, v59 offset:34816
	s_waitcnt vmcnt(13)
	v_mul_f32_e32 v8, 0xbfb8aa3b, v60
	v_exp_f32_e32 v8, v8
	s_nop 0
	v_add_f32_e32 v8, 1.0, v8
	v_rcp_f32_e32 v8, v8
	s_nop 0
	v_mul_f32_e32 v60, v60, v8
	ds_write_b32 v7, v60 offset:36864
	s_waitcnt vmcnt(12)
	v_mul_f32_e32 v8, 0xbfb8aa3b, v61
	v_exp_f32_e32 v8, v8
	s_nop 0
	v_add_f32_e32 v8, 1.0, v8
	v_rcp_f32_e32 v8, v8
	s_nop 0
	v_mul_f32_e32 v61, v61, v8
	ds_write_b32 v7, v61 offset:38912
	s_waitcnt vmcnt(11)
	v_mul_f32_e32 v8, 0xbfb8aa3b, v62
	v_exp_f32_e32 v8, v8
	s_nop 0
	v_add_f32_e32 v8, 1.0, v8
	v_rcp_f32_e32 v8, v8
	s_nop 0
	v_mul_f32_e32 v62, v62, v8
	ds_write_b32 v7, v62 offset:40960
	s_waitcnt vmcnt(10)
	v_mul_f32_e32 v8, 0xbfb8aa3b, v63
	v_exp_f32_e32 v8, v8
	s_nop 0
	v_add_f32_e32 v8, 1.0, v8
	v_rcp_f32_e32 v8, v8
	s_nop 0
	v_mul_f32_e32 v63, v63, v8
	ds_write_b32 v7, v63 offset:43008
	s_waitcnt vmcnt(9)
	v_mul_f32_e32 v8, 0xbfb8aa3b, v64
	v_exp_f32_e32 v8, v8
	s_nop 0
	v_add_f32_e32 v8, 1.0, v8
	v_rcp_f32_e32 v8, v8
	s_nop 0
	v_mul_f32_e32 v64, v64, v8
	ds_write_b32 v7, v64 offset:45056
	s_waitcnt vmcnt(8)
	v_mul_f32_e32 v8, 0xbfb8aa3b, v65
	v_exp_f32_e32 v8, v8
	s_nop 0
	v_add_f32_e32 v8, 1.0, v8
	v_rcp_f32_e32 v8, v8
	s_nop 0
	v_mul_f32_e32 v65, v65, v8
	ds_write_b32 v7, v65 offset:47104
	s_waitcnt vmcnt(7)
	v_mul_f32_e32 v8, 0xbfb8aa3b, v66
	v_exp_f32_e32 v8, v8
	s_nop 0
	v_add_f32_e32 v8, 1.0, v8
	v_rcp_f32_e32 v8, v8
	s_nop 0
	v_mul_f32_e32 v66, v66, v8
	ds_write_b32 v7, v66 offset:49152
	s_waitcnt vmcnt(6)
	v_mul_f32_e32 v8, 0xbfb8aa3b, v67
	v_exp_f32_e32 v8, v8
	s_nop 0
	v_add_f32_e32 v8, 1.0, v8
	v_rcp_f32_e32 v8, v8
	s_nop 0
	v_mul_f32_e32 v67, v67, v8
	ds_write_b32 v7, v67 offset:51200
	s_waitcnt vmcnt(5)
	v_mul_f32_e32 v8, 0xbfb8aa3b, v68
	v_exp_f32_e32 v8, v8
	s_nop 0
	v_add_f32_e32 v8, 1.0, v8
	v_rcp_f32_e32 v8, v8
	s_nop 0
	v_mul_f32_e32 v68, v68, v8
	ds_write_b32 v7, v68 offset:53248
	s_waitcnt vmcnt(4)
	v_mul_f32_e32 v8, 0xbfb8aa3b, v69
	v_exp_f32_e32 v8, v8
	s_nop 0
	v_add_f32_e32 v8, 1.0, v8
	v_rcp_f32_e32 v8, v8
	s_nop 0
	v_mul_f32_e32 v69, v69, v8
	ds_write_b32 v7, v69 offset:55296
	s_waitcnt vmcnt(3)
	v_mul_f32_e32 v8, 0xbfb8aa3b, v70
	v_exp_f32_e32 v8, v8
	s_nop 0
	v_add_f32_e32 v8, 1.0, v8
	v_rcp_f32_e32 v8, v8
	s_nop 0
	v_mul_f32_e32 v70, v70, v8
	ds_write_b32 v7, v70 offset:57344
	s_waitcnt vmcnt(2)
	v_mul_f32_e32 v8, 0xbfb8aa3b, v71
	v_exp_f32_e32 v8, v8
	s_nop 0
	v_add_f32_e32 v8, 1.0, v8
	v_rcp_f32_e32 v8, v8
	s_nop 0
	v_mul_f32_e32 v71, v71, v8
	ds_write_b32 v7, v71 offset:59392
	s_waitcnt vmcnt(1)
	v_mul_f32_e32 v8, 0xbfb8aa3b, v72
	v_exp_f32_e32 v8, v8
	s_nop 0
	v_add_f32_e32 v8, 1.0, v8
	v_rcp_f32_e32 v8, v8
	s_nop 0
	v_mul_f32_e32 v72, v72, v8
	ds_write_b32 v7, v72 offset:61440
	s_waitcnt vmcnt(0)
	v_mul_f32_e32 v8, 0xbfb8aa3b, v73
	v_exp_f32_e32 v8, v8
	s_nop 0
	v_add_f32_e32 v8, 1.0, v8
	v_rcp_f32_e32 v8, v8
	s_nop 0
	v_mul_f32_e32 v73, v73, v8
	ds_write_b32 v7, v73 offset:63488
	s_cmpk_gt_i32 s96, 0x17f
	s_waitcnt lgkmcnt(0)
	s_barrier
; #define LAS __attribute__((address_space(3)))
; __device__ __forceinline__ void p0_mods(const Args& a, LAS unsigned char* lds, int wg, int G, int wave, int lane, int tid) {
;     ...
;     float* mods = (float*)(a.ws + WS_MODS);
;     constexpr int NCH = DEPTH * 6 * D / 64;
;     for (int ch = wg; ch < NCH; ch += G) {
;         const int l = ch / (6 * D / 64), col = (ch % (6 * D / 64)) * 64 + lane;
;         const float* w = a.in[I_WCOND] + (size_t)l * D * 6 * D + col;
;         float acc[4] = {0.f, 0.f, 0.f, 0.f};
;         const LAS float* s0 = sc + (4 * wave) * D;
; #pragma unroll 4
;         for (int d0 = 0; d0 < D; d0 += 4) {
	s_cbranch_scc1 .LBB0_13
	s_add_u32 s2, s16, 0x100000
	s_addc_u32 s3, s17, 0
	s_lshl_b32 s4, s69, 14
	s_lshl_b32 s8, s69, 2
	s_add_i32 s9, s4, 0
	s_add_u32 s10, s84, 0x5a000
	s_addc_u32 s11, s85, 0
	s_mov_b32 s20, 0xfffbe000
	s_mov_b32 s21, 0xfffc4000
	s_mov_b32 s22, 0xfffca000
	s_mov_b32 s23, 0xfffd0000
	s_mov_b32 s24, 0xfffd6000
	s_mov_b32 s25, 0xfffdc000
	s_mov_b32 s28, 0xfffe2000
	s_mov_b32 s29, 0xfffe8000
	s_mov_b32 s30, 0xfffee000
	s_mov_b32 s31, 0xffff4000
	s_movk_i32 s34, 0xa000
	s_mov_b64 s[6:7], 0x60000
	s_movk_i32 s35, 0x6000
	v_mov_b32_e32 v3, 0x6000
	s_mov_b32 s36, s96
